# GEMM unit decode: shift/mask fast path when the row group is full instead of the reciprocal division chain (on top of the in-place quad conversion)
# speedup vs baseline: 1.0069x; 1.0069x over previous
;     __device__ bool next(int i, Unit& u) const {
;         const long L = (long)i * G + c; if (L >= nwg) return false;
;         int wgid = (int)L; { const int q = nwg / NXCD, r = nwg % NXCD, xcd = wgid % NXCD, off = wgid / NXCD; wgid = (xcd < r ? xcd * (q + 1) : r * (q + 1) + (xcd - r) * q) + off; }
;         const int nig = wgm * nN, gid = wgid / nig, fm = gid * wgm, gsz = (nM - fm) < wgm ? (nM - fm) : wgm;
;         u.pm = fm + ((wgid % nig) % gsz); u.pn = (wgid % nig) / gsz; u.e = tile_e ? (int)tile_e[u.pm] : 0; return true;
.LBB0_153:
	v_readlane_b32 s38, v254, 35
	s_add_i32 s72, s46, 1
	v_readlane_b32 s39, v254, 36
	s_mul_i32 s23, s72, s39
	s_mul_hi_u32 s37, s72, s38
	s_add_i32 s37, s37, s23
	s_mul_i32 s23, s72, s38
	s_add_u32 s42, s23, s96
	s_addc_u32 s43, s37, s97
	v_mov_b64_e32 v[0:1], 0xb00
	v_cmp_lt_i64_e64 s[38:39], s[42:43], v[0:1]
	v_mov_b64_e32 v[0:1], 0xaff
	v_cmp_gt_i64_e32 vcc, s[42:43], v[0:1]
	s_cbranch_vccnz .LBB0_155
	s_ashr_i32 s22, s42, 31
	s_lshr_b32 s22, s22, 29
	s_add_i32 s22, s42, s22
	s_ashr_i32 s23, s22, 3
	s_and_b32 s22, s22, -8
	s_sub_i32 s22, s42, s22
	s_cmp_lt_i32 s22, 0
	s_movk_i32 s36, 0x161
	s_cselect_b32 s36, s36, 0x160
	s_mul_i32 s22, s22, s36
	s_add_i32 s22, s22, s23
	s_mul_hi_i32 s23, s22, 0x2e8ba2e9
	s_lshr_b32 s36, s23, 31
	s_ashr_i32 s23, s23, 4
	s_add_i32 s23, s23, s36
	s_lshl_b32 s36, s23, 3
	s_sub_i32 s37, 0x100, s36
	s_min_i32 s37, s37, 8
	s_mulk_i32 s23, 0x58
	s_sub_i32 s23, s22, s23
	s_cmp_eq_u32 s37, 8
	s_cbranch_scc0 .Ldivg_inproj
	s_lshr_b32 s22, s23, 3
	s_and_b32 s23, s23, 7
	s_branch .Ldivj_inproj
.Ldivg_inproj:
	s_abs_i32 s42, s37
	v_cvt_f32_u32_e32 v0, s42
	s_sub_i32 s44, 0, s42
	v_rcp_iflag_f32_e32 v0, v0
	s_abs_i32 s22, s23
	s_xor_b32 s43, s23, s37
	s_ashr_i32 s43, s43, 31
	v_mul_f32_e32 v0, 0x4f7ffffe, v0
	v_cvt_u32_f32_e32 v0, v0
	s_nop 0
	v_readfirstlane_b32 s45, v0
	s_mul_i32 s44, s44, s45
	s_mul_hi_u32 s44, s45, s44
	s_add_i32 s45, s45, s44
	s_mul_hi_u32 s44, s22, s45
	s_mul_i32 s45, s44, s42
	s_sub_i32 s22, s22, s45
	s_add_i32 s47, s44, 1
	s_sub_i32 s45, s22, s42
	s_cmp_ge_u32 s22, s42
	s_cselect_b32 s44, s47, s44
	s_cselect_b32 s22, s45, s22
	s_add_i32 s45, s44, 1
	s_cmp_ge_u32 s22, s42
	s_cselect_b32 s22, s45, s44
	s_xor_b32 s22, s22, s43
	s_sub_i32 s22, s22, s43
	s_mul_i32 s37, s22, s37
	s_sub_i32 s23, s23, s37
.Ldivj_inproj:
	s_add_i32 s36, s36, s23

;     __device__ bool next(int i, Unit& u) const {
;     ...
;         int wgid = (int)L; { const int q = nwg / NXCD, r = nwg % NXCD, xcd = wgid % NXCD, off = wgid / NXCD; wgid = (xcd < r ? xcd * (q + 1) : r * (q + 1) + (xcd - r) * q) + off; }
;         const int nig = wgm * nN, gid = wgid / nig, fm = gid * wgm, gsz = (nM - fm) < wgm ? (nM - fm) : wgm;
;         u.pm = fm + ((wgid % nig) % gsz); u.pn = (wgid % nig) / gsz; u.e = tile_e ? (int)tile_e[u.pm] : 0; return true;
.LBB0_718:
	s_ashr_i32 s22, s36, 3
	s_add_i32 s22, s42, s22
	s_ashr_i32 s23, s22, 31
	s_lshr_b32 s23, s23, 27
	s_add_i32 s23, s22, s23
	s_ashr_i32 s36, s23, 5
	s_lshl_b32 s36, s36, 3
	s_sub_i32 s37, 0x100, s36
	s_min_i32 s37, s37, 8
	s_andn2_b32 s23, s23, 31
	s_sub_i32 s23, s22, s23
	s_cmp_eq_u32 s37, 8
	s_cbranch_scc0 .Ldivg_outproj
	s_lshr_b32 s22, s23, 3
	s_and_b32 s23, s23, 7
	s_branch .Ldivj_outproj

;     __device__ bool next(int i, Unit& u) const {
;         const long L = (long)i * G + c; if (L >= nwg) return false;
;         int wgid = (int)L; { const int q = nwg / NXCD, r = nwg % NXCD, xcd = wgid % NXCD, off = wgid / NXCD; wgid = (xcd < r ? xcd * (q + 1) : r * (q + 1) + (xcd - r) * q) + off; }
;         const int nig = wgm * nN, gid = wgid / nig, fm = gid * wgm, gsz = (nM - fm) < wgm ? (nM - fm) : wgm;
;         u.pm = fm + ((wgid % nig) % gsz); u.pn = (wgid % nig) / gsz; u.e = tile_e ? (int)tile_e[u.pm] : 0; return true;
.LBB0_996:
	v_readlane_b32 s42, v254, 35
	s_add_i32 s90, s35, 1
	v_readlane_b32 s43, v254, 36
	s_mul_i32 s3, s90, s43
	s_mul_hi_u32 s8, s90, s42
	s_add_i32 s3, s8, s3
	s_mul_i32 s8, s90, s42
	s_add_u32 s8, s8, s96
	s_addc_u32 s9, s3, s97
	v_mov_b64_e32 v[0:1], s[22:23]
	v_cmp_ge_i64_e32 vcc, s[8:9], v[0:1]
	v_cmp_lt_i64_e64 s[44:45], s[8:9], v[0:1]
	s_mov_b64 s[42:43], 0
	s_cbranch_vccnz .LBB0_998
	s_ashr_i32 s3, s8, 31
	s_lshr_b32 s3, s3, 29
	s_add_i32 s3, s8, s3
	s_ashr_i32 s9, s3, 3
	s_and_b32 s3, s3, -8
	s_sub_i32 s3, s8, s3
	s_lshr_b32 s8, s3, 31
	s_add_i32 s8, s21, s8
	s_mul_i32 s3, s8, s3
	s_add_i32 s3, s3, s9
	s_ashr_i32 s8, s3, 31
	s_lshr_b32 s8, s8, 26
	s_add_i32 s8, s3, s8
	s_ashr_i32 s9, s8, 6
	s_lshl_b32 s9, s9, 3
	s_sub_i32 s34, s21, s9
	s_min_i32 s34, s34, 8
	s_andn2_b32 s8, s8, 63
	s_sub_i32 s3, s3, s8
	s_cmp_eq_u32 s34, 8
	s_cbranch_scc0 .Ldivg_g1
	s_lshr_b32 s52, s3, 3
	s_and_b32 s3, s3, 7
	s_branch .Ldivj_g1
.Ldivg_g1:
	s_abs_i32 s42, s34
	v_cvt_f32_u32_e32 v0, s42
	s_sub_i32 s52, 0, s42
	v_rcp_iflag_f32_e32 v0, v0
	s_abs_i32 s8, s3
	s_xor_b32 s43, s3, s34
	s_ashr_i32 s43, s43, 31
	v_mul_f32_e32 v0, 0x4f7ffffe, v0
	v_cvt_u32_f32_e32 v0, v0
	s_nop 0
	v_readfirstlane_b32 s53, v0
	s_mul_i32 s52, s52, s53
	s_mul_hi_u32 s52, s53, s52
	s_add_i32 s53, s53, s52
	s_mul_hi_u32 s52, s8, s53
	s_mul_i32 s53, s52, s42
	s_sub_i32 s8, s8, s53
	s_add_i32 s54, s52, 1
	s_sub_i32 s53, s8, s42
	s_cmp_ge_u32 s8, s42
	s_cselect_b32 s52, s54, s52
	s_cselect_b32 s8, s53, s8
	s_add_i32 s53, s52, 1
	s_cmp_ge_u32 s8, s42
	s_cselect_b32 s8, s53, s52
	s_xor_b32 s8, s8, s43
	s_sub_i32 s52, s8, s43
	s_mul_i32 s8, s52, s34
	s_sub_i32 s3, s3, s8
.Ldivj_g1:
	s_add_i32 s54, s3, s9
	s_lshl_b32 s3, s54, 1
	s_add_i32 s3, s3, 0
	s_add_i32 s3, s3, 0x20600
	v_mov_b32_e32 v0, s3
	ds_read_u16 v0, v0
	s_mov_b64 s[42:43], s[46:47]
	s_waitcnt lgkmcnt(0)
	v_readfirstlane_b32 s56, v0

;     __device__ bool next(int i, Unit& u) const {
;     ...
;         int wgid = (int)L; { const int q = nwg / NXCD, r = nwg % NXCD, xcd = wgid % NXCD, off = wgid / NXCD; wgid = (xcd < r ? xcd * (q + 1) : r * (q + 1) + (xcd - r) * q) + off; }
;         const int nig = wgm * nN, gid = wgid / nig, fm = gid * wgm, gsz = (nM - fm) < wgm ? (nM - fm) : wgm;
;         u.pm = fm + ((wgid % nig) % gsz); u.pn = (wgid % nig) / gsz; u.e = tile_e ? (int)tile_e[u.pm] : 0; return true;
.LBB0_1107:
	s_ashr_i32 s3, s3, 3
	s_add_i32 s3, s49, s3
	s_ashr_i32 s36, s3, 31
	s_lshr_b32 s36, s36, 27
	s_add_i32 s36, s3, s36
	s_ashr_i32 s37, s36, 5
	s_lshl_b32 s37, s37, 3
	s_sub_i32 s48, s21, s37
	s_min_i32 s48, s48, 8
	s_andn2_b32 s36, s36, 31
	s_sub_i32 s3, s3, s36
	s_cmp_eq_u32 s48, 8
	s_cbranch_scc0 .Ldivg_g2
	s_lshr_b32 s36, s3, 3
	s_and_b32 s3, s3, 7
	s_branch .Ldivj_g2
.Ldivg_g2:
	s_abs_i32 s49, s48
	v_cvt_f32_u32_e32 v0, s49
	s_sub_i32 s51, 0, s49
	v_rcp_iflag_f32_e32 v0, v0
	s_abs_i32 s36, s3
	s_xor_b32 s50, s3, s48
	s_ashr_i32 s50, s50, 31
	v_mul_f32_e32 v0, 0x4f7ffffe, v0
	v_cvt_u32_f32_e32 v0, v0
	s_nop 0
	v_readfirstlane_b32 s52, v0
	s_mul_i32 s51, s51, s52
	s_mul_hi_u32 s51, s52, s51
	s_add_i32 s52, s52, s51
	s_mul_hi_u32 s51, s36, s52
	s_mul_i32 s52, s51, s49
	s_sub_i32 s36, s36, s52
	s_add_i32 s53, s51, 1
	s_sub_i32 s52, s36, s49
	s_cmp_ge_u32 s36, s49
	s_cselect_b32 s51, s53, s51
	s_cselect_b32 s36, s52, s36
	s_add_i32 s52, s51, 1
	s_cmp_ge_u32 s36, s49
	s_cselect_b32 s36, s52, s51
	s_xor_b32 s36, s36, s50
	s_sub_i32 s36, s36, s50
	s_mul_i32 s48, s36, s48
	s_sub_i32 s3, s3, s48
.Ldivj_g2:
	s_add_i32 s48, s37, s3
	s_sub_i32 s48, s21, s48
	s_add_i32 s48, s48, -1
	s_lshl_b32 s3, s48, 1
	s_add_i32 s3, s3, 0
	s_add_i32 s3, s3, 0x20600
	v_mov_b32_e32 v0, s3
	ds_read_u16 v0, v0
	s_waitcnt lgkmcnt(0)
	v_readfirstlane_b32 s50, v0
